# hand-written EpiP with the two decay logs fetched by scalar loads (no vmcnt drain at the epilogue start); P1 per-ms modulation vectors shared through LDS
# speedup vs baseline: 1.0186x; 1.0007x over previous
; __device__ __forceinline__ float ex2(float x) { return __builtin_amdgcn_exp2f(x); }
; __device__ __forceinline__ u32x4 pack8(const f32x4 a, const f32x4 b) { u32x4 w; w.x = pk2(a[0], a[1]); w.y = pk2(a[2], a[3]); w.z = pk2(b[0], b[1]); w.w = pk2(b[2], b[3]); return w; }
;     __device__ __forceinline__ bool operator()(EPI_ARGS) const {
;         const int h = u.z; const float lgf = dec[h], lgb = dec[4 + h];
; #pragma unroll
;         for (int ai = 0; ai < 2; ++ai)
; #pragma unroll
;             for (int m = 0; m < 4; ++m) {
;                 const int il = ROWLOC(ai, m), i = u.pm * 256 + il;
; #pragma unroll
;                 for (int bj = 0; bj < 2; ++bj) {
;                     const int j0 = u.w * 256 + COLLOC(bj);
;                     f32x4 p[2];
; #pragma unroll
;                     for (int n = 0; n < 2; ++n)
; #pragma unroll
;                         for (int e = 0; e < 4; ++e) { const int d = i - (j0 + 4 * n + e); const float w = ex2(d >= 0 ? (float)d * lgf : (float)(-d) * lgb); p[n][e] = acc[ai][bj][m][n][e] * w; }
;                     *(u32x4*)(pscr + (size_t)il * D + j0) = pack8(p[0], p[1]);
;                 }
;             }
.LBB0_833:
	v_mov_b32_e32 v130, v145
	v_mov_b32_e32 v131, v146
	s_cmp_lt_i32 s35, 2
	s_cselect_b32 s58, s72, s58
	s_cselect_b32 s33, s50, s33
	s_cselect_b32 s34, s35, s34
	s_ashr_i32 s59, s58, 31
	s_lshl_b64 s[16:17], s[58:59], 2
	s_add_u32 s16, s4, s16
	s_addc_u32 s17, s5, s17
	s_load_dword s98, s[16:17], 0x0
	s_load_dword s100, s[16:17], 0x10
	s_lshl_b32 s17, s34, 8
	v_add_u32_e32 v138, s68, v130
	s_lshl_b32 s16, s33, 8
	s_or_b32 s17, s17, s64
	v_add_u32_e32 v153, s16, v138
	v_lshl_add_u32 v140, v131, 3, s17
	v_sub_u32_e32 v130, v153, v140
	v_cvt_f32_i32_e32 v178, v130
	v_lshlrev_b32_e32 v196, 11, v138
	v_lshl_add_u32 v196, v140, 1, v196
	s_nop 0
	v_add_f32_e32 v179, -1.0, v178
	v_add_f32_e32 v180, -2.0, v178
	v_add_f32_e32 v181, 0xc0400000, v178
	v_add_f32_e32 v182, -4.0, v178
	v_add_f32_e32 v183, 0xc0a00000, v178
	v_add_f32_e32 v184, 0xc0c00000, v178
	v_add_f32_e32 v185, 0xc0e00000, v178
	s_waitcnt lgkmcnt(0)
	v_mov_b32_e32 v149, s98
	s_xor_b32 s100, s100, 0x80000000
	s_cmp_ge_i32 s33, s34
	s_cselect_b32 s99, s98, s100
	s_cmp_gt_i32 s33, s34
	s_cselect_b32 s101, s98, s100
	v_mov_b32_e32 v158, s99
	v_mov_b32_e32 v160, s101
	v_mov_b32_e32 v162, s100
	v_mov_b32_e32 v197, v196
	v_add_u32_e32 v198, 0x40000, v196
	s_mov_b32 s16, 0x00000000
	v_pk_add_f32 v[186:187], v[178:179], s[16:17] op_sel_hi:[1,0]
	v_pk_add_f32 v[188:189], v[180:181], s[16:17] op_sel_hi:[1,0]
	v_pk_add_f32 v[190:191], v[182:183], s[16:17] op_sel_hi:[1,0]
	v_pk_add_f32 v[192:193], v[184:185], s[16:17] op_sel_hi:[1,0]
	v_cmp_gt_f32_e32 vcc, 0, v186
	s_nop 1
	v_cndmask_b32_e32 v194, v149, v162, vcc
	v_cmp_gt_f32_e32 vcc, 0, v187
	v_mul_f32_e32 v186, v186, v194
	s_nop 0
	v_cndmask_b32_e32 v195, v149, v162, vcc
	v_cmp_gt_f32_e32 vcc, 0, v188
	v_mul_f32_e32 v187, v187, v195
	s_nop 0
	v_cndmask_b32_e32 v194, v149, v162, vcc
	v_cmp_gt_f32_e32 vcc, 0, v189
	v_mul_f32_e32 v188, v188, v194
	s_nop 0
	v_cndmask_b32_e32 v195, v149, v162, vcc
	v_cmp_gt_f32_e32 vcc, 0, v190
	v_mul_f32_e32 v189, v189, v195
	s_nop 0
	v_cndmask_b32_e32 v194, v149, v162, vcc
	v_cmp_gt_f32_e32 vcc, 0, v191
	v_mul_f32_e32 v190, v190, v194
	s_nop 0
	v_cndmask_b32_e32 v195, v149, v162, vcc
	v_cmp_gt_f32_e32 vcc, 0, v192
	v_mul_f32_e32 v191, v191, v195
	s_nop 0
	v_cndmask_b32_e32 v194, v149, v162, vcc
	v_cmp_gt_f32_e32 vcc, 0, v193
	v_mul_f32_e32 v192, v192, v194
	s_nop 0
	v_cndmask_b32_e32 v195, v149, v162, vcc
	v_mul_f32_e32 v193, v193, v195
	v_exp_f32_e32 v186, v186
	v_exp_f32_e32 v187, v187
	v_exp_f32_e32 v188, v188
	v_exp_f32_e32 v189, v189
	v_exp_f32_e32 v190, v190
	v_exp_f32_e32 v191, v191
	v_exp_f32_e32 v192, v192
	v_exp_f32_e32 v193, v193
	v_pk_mul_f32 v[124:125], v[124:125], v[186:187]
	v_pk_mul_f32 v[126:127], v[126:127], v[188:189]
	v_pk_mul_f32 v[120:121], v[120:121], v[190:191]
	v_pk_mul_f32 v[122:123], v[122:123], v[192:193]
	v_cvt_pk_bf16_f32 v124, v124, v125
	v_cvt_pk_bf16_f32 v125, v126, v127
	v_cvt_pk_bf16_f32 v126, v120, v121
	v_cvt_pk_bf16_f32 v127, v122, v123
	global_store_dwordx4 v197, v[124:127], s[80:81]
	v_pk_mul_f32 v[52:53], v[52:53], v[186:187]
	v_pk_mul_f32 v[54:55], v[54:55], v[188:189]
	v_pk_mul_f32 v[48:49], v[48:49], v[190:191]
	v_pk_mul_f32 v[50:51], v[50:51], v[192:193]
	v_cvt_pk_bf16_f32 v52, v52, v53
	v_cvt_pk_bf16_f32 v53, v54, v55
	v_cvt_pk_bf16_f32 v54, v48, v49
	v_cvt_pk_bf16_f32 v55, v50, v51
	global_store_dwordx4 v198, v[52:55], s[80:81] offset:256
	s_mov_b32 s16, 0x43000000
	v_pk_add_f32 v[186:187], v[178:179], s[16:17] op_sel_hi:[1,0]
	v_pk_add_f32 v[188:189], v[180:181], s[16:17] op_sel_hi:[1,0]
	v_pk_add_f32 v[190:191], v[182:183], s[16:17] op_sel_hi:[1,0]
	v_pk_add_f32 v[192:193], v[184:185], s[16:17] op_sel_hi:[1,0]
	v_pk_mul_f32 v[186:187], v[186:187], v[158:159] op_sel_hi:[1,0]
	v_pk_mul_f32 v[188:189], v[188:189], v[158:159] op_sel_hi:[1,0]
	v_pk_mul_f32 v[190:191], v[190:191], v[158:159] op_sel_hi:[1,0]
	v_pk_mul_f32 v[192:193], v[192:193], v[158:159] op_sel_hi:[1,0]
	v_exp_f32_e32 v186, v186
	v_exp_f32_e32 v187, v187
	v_exp_f32_e32 v188, v188
	v_exp_f32_e32 v189, v189
	v_exp_f32_e32 v190, v190
	v_exp_f32_e32 v191, v191
	v_exp_f32_e32 v192, v192
	v_exp_f32_e32 v193, v193
	v_pk_mul_f32 v[60:61], v[60:61], v[186:187]
	v_pk_mul_f32 v[62:63], v[62:63], v[188:189]
	v_pk_mul_f32 v[56:57], v[56:57], v[190:191]
	v_pk_mul_f32 v[58:59], v[58:59], v[192:193]
	v_cvt_pk_bf16_f32 v60, v60, v61
	v_cvt_pk_bf16_f32 v61, v62, v63
	v_cvt_pk_bf16_f32 v62, v56, v57
	v_cvt_pk_bf16_f32 v63, v58, v59
	global_store_dwordx4 v198, v[60:63], s[80:81]
	s_mov_b32 s16, 0xc3000000
	v_pk_add_f32 v[186:187], v[178:179], s[16:17] op_sel_hi:[1,0]
	v_pk_add_f32 v[188:189], v[180:181], s[16:17] op_sel_hi:[1,0]
	v_pk_add_f32 v[190:191], v[182:183], s[16:17] op_sel_hi:[1,0]
	v_pk_add_f32 v[192:193], v[184:185], s[16:17] op_sel_hi:[1,0]
	v_pk_mul_f32 v[186:187], v[186:187], v[160:161] op_sel_hi:[1,0]
	v_pk_mul_f32 v[188:189], v[188:189], v[160:161] op_sel_hi:[1,0]
	v_pk_mul_f32 v[190:191], v[190:191], v[160:161] op_sel_hi:[1,0]
	v_pk_mul_f32 v[192:193], v[192:193], v[160:161] op_sel_hi:[1,0]
	v_exp_f32_e32 v186, v186
	v_exp_f32_e32 v187, v187
	v_exp_f32_e32 v188, v188
	v_exp_f32_e32 v189, v189
	v_exp_f32_e32 v190, v190
	v_exp_f32_e32 v191, v191
	v_exp_f32_e32 v192, v192
	v_exp_f32_e32 v193, v193
	v_pk_mul_f32 v[116:117], v[116:117], v[186:187]
	v_pk_mul_f32 v[118:119], v[118:119], v[188:189]
	v_pk_mul_f32 v[112:113], v[112:113], v[190:191]
	v_pk_mul_f32 v[114:115], v[114:115], v[192:193]
	v_cvt_pk_bf16_f32 v116, v116, v117
	v_cvt_pk_bf16_f32 v117, v118, v119
	v_cvt_pk_bf16_f32 v118, v112, v113
	v_cvt_pk_bf16_f32 v119, v114, v115
	global_store_dwordx4 v197, v[116:119], s[80:81] offset:256
; __device__ __forceinline__ float ex2(float x) { return __builtin_amdgcn_exp2f(x); }
; __device__ __forceinline__ u32x4 pack8(const f32x4 a, const f32x4 b) { u32x4 w; w.x = pk2(a[0], a[1]); w.y = pk2(a[2], a[3]); w.z = pk2(b[0], b[1]); w.w = pk2(b[2], b[3]); return w; }
;     __device__ __forceinline__ bool operator()(EPI_ARGS) const {
;     ...
;                 const int il = ROWLOC(ai, m), i = u.pm * 256 + il;
; #pragma unroll
;                 for (int bj = 0; bj < 2; ++bj) {
;                     const int j0 = u.w * 256 + COLLOC(bj);
;                     f32x4 p[2];
; #pragma unroll
;                     for (int n = 0; n < 2; ++n)
; #pragma unroll
;                         for (int e = 0; e < 4; ++e) { const int d = i - (j0 + 4 * n + e); const float w = ex2(d >= 0 ? (float)d * lgf : (float)(-d) * lgb); p[n][e] = acc[ai][bj][m][n][e] * w; }
;                     *(u32x4*)(pscr + (size_t)il * D + j0) = pack8(p[0], p[1]);
;                 }
	v_add_u32_e32 v199, 0x8000, v196
	v_add_u32_e32 v200, 0x48000, v196
	s_mov_b32 s16, 0x41800000
	v_pk_add_f32 v[186:187], v[178:179], s[16:17] op_sel_hi:[1,0]
	v_pk_add_f32 v[188:189], v[180:181], s[16:17] op_sel_hi:[1,0]
	v_pk_add_f32 v[190:191], v[182:183], s[16:17] op_sel_hi:[1,0]
	v_pk_add_f32 v[192:193], v[184:185], s[16:17] op_sel_hi:[1,0]
	v_cmp_gt_f32_e32 vcc, 0, v186
	s_nop 1
	v_cndmask_b32_e32 v194, v149, v162, vcc
	v_cmp_gt_f32_e32 vcc, 0, v187
	v_mul_f32_e32 v186, v186, v194
	s_nop 0
	v_cndmask_b32_e32 v195, v149, v162, vcc
	v_cmp_gt_f32_e32 vcc, 0, v188
	v_mul_f32_e32 v187, v187, v195
	s_nop 0
	v_cndmask_b32_e32 v194, v149, v162, vcc
	v_cmp_gt_f32_e32 vcc, 0, v189
	v_mul_f32_e32 v188, v188, v194
	s_nop 0
	v_cndmask_b32_e32 v195, v149, v162, vcc
	v_cmp_gt_f32_e32 vcc, 0, v190
	v_mul_f32_e32 v189, v189, v195
	s_nop 0
	v_cndmask_b32_e32 v194, v149, v162, vcc
	v_cmp_gt_f32_e32 vcc, 0, v191
	v_mul_f32_e32 v190, v190, v194
	s_nop 0
	v_cndmask_b32_e32 v195, v149, v162, vcc
	v_cmp_gt_f32_e32 vcc, 0, v192
	v_mul_f32_e32 v191, v191, v195
	s_nop 0
	v_cndmask_b32_e32 v194, v149, v162, vcc
	v_cmp_gt_f32_e32 vcc, 0, v193
	v_mul_f32_e32 v192, v192, v194
	s_nop 0
	v_cndmask_b32_e32 v195, v149, v162, vcc
	v_mul_f32_e32 v193, v193, v195
	v_exp_f32_e32 v186, v186
	v_exp_f32_e32 v187, v187
	v_exp_f32_e32 v188, v188
	v_exp_f32_e32 v189, v189
	v_exp_f32_e32 v190, v190
	v_exp_f32_e32 v191, v191
	v_exp_f32_e32 v192, v192
	v_exp_f32_e32 v193, v193
	v_pk_mul_f32 v[108:109], v[108:109], v[186:187]
	v_pk_mul_f32 v[110:111], v[110:111], v[188:189]
	v_pk_mul_f32 v[104:105], v[104:105], v[190:191]
	v_pk_mul_f32 v[106:107], v[106:107], v[192:193]
	v_cvt_pk_bf16_f32 v108, v108, v109
	v_cvt_pk_bf16_f32 v109, v110, v111
	v_cvt_pk_bf16_f32 v110, v104, v105
	v_cvt_pk_bf16_f32 v111, v106, v107
	global_store_dwordx4 v199, v[108:111], s[80:81]
	v_pk_mul_f32 v[36:37], v[36:37], v[186:187]
	v_pk_mul_f32 v[38:39], v[38:39], v[188:189]
	v_pk_mul_f32 v[32:33], v[32:33], v[190:191]
	v_pk_mul_f32 v[34:35], v[34:35], v[192:193]
	v_cvt_pk_bf16_f32 v36, v36, v37
	v_cvt_pk_bf16_f32 v37, v38, v39
	v_cvt_pk_bf16_f32 v38, v32, v33
	v_cvt_pk_bf16_f32 v39, v34, v35
	global_store_dwordx4 v200, v[36:39], s[80:81] offset:256
	s_mov_b32 s16, 0x43100000
	v_pk_add_f32 v[186:187], v[178:179], s[16:17] op_sel_hi:[1,0]
	v_pk_add_f32 v[188:189], v[180:181], s[16:17] op_sel_hi:[1,0]
	v_pk_add_f32 v[190:191], v[182:183], s[16:17] op_sel_hi:[1,0]
	v_pk_add_f32 v[192:193], v[184:185], s[16:17] op_sel_hi:[1,0]
	v_pk_mul_f32 v[186:187], v[186:187], v[158:159] op_sel_hi:[1,0]
	v_pk_mul_f32 v[188:189], v[188:189], v[158:159] op_sel_hi:[1,0]
	v_pk_mul_f32 v[190:191], v[190:191], v[158:159] op_sel_hi:[1,0]
	v_pk_mul_f32 v[192:193], v[192:193], v[158:159] op_sel_hi:[1,0]
	v_exp_f32_e32 v186, v186
	v_exp_f32_e32 v187, v187
	v_exp_f32_e32 v188, v188
	v_exp_f32_e32 v189, v189
	v_exp_f32_e32 v190, v190
	v_exp_f32_e32 v191, v191
	v_exp_f32_e32 v192, v192
	v_exp_f32_e32 v193, v193
	v_pk_mul_f32 v[44:45], v[44:45], v[186:187]
	v_pk_mul_f32 v[46:47], v[46:47], v[188:189]
	v_pk_mul_f32 v[40:41], v[40:41], v[190:191]
	v_pk_mul_f32 v[42:43], v[42:43], v[192:193]
	v_cvt_pk_bf16_f32 v44, v44, v45
	v_cvt_pk_bf16_f32 v45, v46, v47
	v_cvt_pk_bf16_f32 v46, v40, v41
	v_cvt_pk_bf16_f32 v47, v42, v43
	global_store_dwordx4 v200, v[44:47], s[80:81]
	s_mov_b32 s16, 0xc2e00000
	v_pk_add_f32 v[186:187], v[178:179], s[16:17] op_sel_hi:[1,0]
	v_pk_add_f32 v[188:189], v[180:181], s[16:17] op_sel_hi:[1,0]
	v_pk_add_f32 v[190:191], v[182:183], s[16:17] op_sel_hi:[1,0]
	v_pk_add_f32 v[192:193], v[184:185], s[16:17] op_sel_hi:[1,0]
	v_pk_mul_f32 v[186:187], v[186:187], v[160:161] op_sel_hi:[1,0]
	v_pk_mul_f32 v[188:189], v[188:189], v[160:161] op_sel_hi:[1,0]
	v_pk_mul_f32 v[190:191], v[190:191], v[160:161] op_sel_hi:[1,0]
	v_pk_mul_f32 v[192:193], v[192:193], v[160:161] op_sel_hi:[1,0]
	v_exp_f32_e32 v186, v186
	v_exp_f32_e32 v187, v187
	v_exp_f32_e32 v188, v188
	v_exp_f32_e32 v189, v189
	v_exp_f32_e32 v190, v190
	v_exp_f32_e32 v191, v191
	v_exp_f32_e32 v192, v192
	v_exp_f32_e32 v193, v193
	v_pk_mul_f32 v[100:101], v[100:101], v[186:187]
	v_pk_mul_f32 v[102:103], v[102:103], v[188:189]
	v_pk_mul_f32 v[96:97], v[96:97], v[190:191]
	v_pk_mul_f32 v[98:99], v[98:99], v[192:193]
	v_cvt_pk_bf16_f32 v100, v100, v101
	v_cvt_pk_bf16_f32 v101, v102, v103
	v_cvt_pk_bf16_f32 v102, v96, v97
	v_cvt_pk_bf16_f32 v103, v98, v99
	global_store_dwordx4 v199, v[100:103], s[80:81] offset:256
	v_add_u32_e32 v201, 0x10000, v196
	v_add_u32_e32 v202, 0x50000, v196
	s_mov_b32 s16, 0x42000000
	v_pk_add_f32 v[186:187], v[178:179], s[16:17] op_sel_hi:[1,0]
	v_pk_add_f32 v[188:189], v[180:181], s[16:17] op_sel_hi:[1,0]
	v_pk_add_f32 v[190:191], v[182:183], s[16:17] op_sel_hi:[1,0]
	v_pk_add_f32 v[192:193], v[184:185], s[16:17] op_sel_hi:[1,0]
	v_cmp_gt_f32_e32 vcc, 0, v186
	s_nop 1
	v_cndmask_b32_e32 v194, v149, v162, vcc
	v_cmp_gt_f32_e32 vcc, 0, v187
	v_mul_f32_e32 v186, v186, v194
	s_nop 0
	v_cndmask_b32_e32 v195, v149, v162, vcc
	v_cmp_gt_f32_e32 vcc, 0, v188
	v_mul_f32_e32 v187, v187, v195
	s_nop 0
	v_cndmask_b32_e32 v194, v149, v162, vcc
	v_cmp_gt_f32_e32 vcc, 0, v189
	v_mul_f32_e32 v188, v188, v194
	s_nop 0
	v_cndmask_b32_e32 v195, v149, v162, vcc
	v_cmp_gt_f32_e32 vcc, 0, v190
	v_mul_f32_e32 v189, v189, v195
	s_nop 0
	v_cndmask_b32_e32 v194, v149, v162, vcc
	v_cmp_gt_f32_e32 vcc, 0, v191
	v_mul_f32_e32 v190, v190, v194
	s_nop 0
	v_cndmask_b32_e32 v195, v149, v162, vcc
	v_cmp_gt_f32_e32 vcc, 0, v192
	v_mul_f32_e32 v191, v191, v195
	s_nop 0
	v_cndmask_b32_e32 v194, v149, v162, vcc
	v_cmp_gt_f32_e32 vcc, 0, v193
	v_mul_f32_e32 v192, v192, v194
	s_nop 0
; __device__ __forceinline__ float ex2(float x) { return __builtin_amdgcn_exp2f(x); }
; __device__ __forceinline__ u32x4 pack8(const f32x4 a, const f32x4 b) { u32x4 w; w.x = pk2(a[0], a[1]); w.y = pk2(a[2], a[3]); w.z = pk2(b[0], b[1]); w.w = pk2(b[2], b[3]); return w; }
;     __device__ __forceinline__ bool operator()(EPI_ARGS) const {
;     ...
;                 const int il = ROWLOC(ai, m), i = u.pm * 256 + il;
; #pragma unroll
;                 for (int bj = 0; bj < 2; ++bj) {
;                     const int j0 = u.w * 256 + COLLOC(bj);
;                     f32x4 p[2];
; #pragma unroll
;                     for (int n = 0; n < 2; ++n)
; #pragma unroll
;                         for (int e = 0; e < 4; ++e) { const int d = i - (j0 + 4 * n + e); const float w = ex2(d >= 0 ? (float)d * lgf : (float)(-d) * lgb); p[n][e] = acc[ai][bj][m][n][e] * w; }
;                     *(u32x4*)(pscr + (size_t)il * D + j0) = pack8(p[0], p[1]);
;                 }
	v_cndmask_b32_e32 v195, v149, v162, vcc
	v_mul_f32_e32 v193, v193, v195
	v_exp_f32_e32 v186, v186
	v_exp_f32_e32 v187, v187
	v_exp_f32_e32 v188, v188
	v_exp_f32_e32 v189, v189
	v_exp_f32_e32 v190, v190
	v_exp_f32_e32 v191, v191
	v_exp_f32_e32 v192, v192
	v_exp_f32_e32 v193, v193
	v_pk_mul_f32 v[92:93], v[92:93], v[186:187]
	v_pk_mul_f32 v[94:95], v[94:95], v[188:189]
	v_pk_mul_f32 v[88:89], v[88:89], v[190:191]
	v_pk_mul_f32 v[90:91], v[90:91], v[192:193]
	v_cvt_pk_bf16_f32 v92, v92, v93
	v_cvt_pk_bf16_f32 v93, v94, v95
	v_cvt_pk_bf16_f32 v94, v88, v89
	v_cvt_pk_bf16_f32 v95, v90, v91
	global_store_dwordx4 v201, v[92:95], s[80:81]
	v_pk_mul_f32 v[20:21], v[20:21], v[186:187]
	v_pk_mul_f32 v[22:23], v[22:23], v[188:189]
	v_pk_mul_f32 v[16:17], v[16:17], v[190:191]
	v_pk_mul_f32 v[18:19], v[18:19], v[192:193]
	v_cvt_pk_bf16_f32 v20, v20, v21
	v_cvt_pk_bf16_f32 v21, v22, v23
	v_cvt_pk_bf16_f32 v22, v16, v17
	v_cvt_pk_bf16_f32 v23, v18, v19
	global_store_dwordx4 v202, v[20:23], s[80:81] offset:256
	s_mov_b32 s16, 0x43200000
	v_pk_add_f32 v[186:187], v[178:179], s[16:17] op_sel_hi:[1,0]
	v_pk_add_f32 v[188:189], v[180:181], s[16:17] op_sel_hi:[1,0]
	v_pk_add_f32 v[190:191], v[182:183], s[16:17] op_sel_hi:[1,0]
	v_pk_add_f32 v[192:193], v[184:185], s[16:17] op_sel_hi:[1,0]
	v_pk_mul_f32 v[186:187], v[186:187], v[158:159] op_sel_hi:[1,0]
	v_pk_mul_f32 v[188:189], v[188:189], v[158:159] op_sel_hi:[1,0]
	v_pk_mul_f32 v[190:191], v[190:191], v[158:159] op_sel_hi:[1,0]
	v_pk_mul_f32 v[192:193], v[192:193], v[158:159] op_sel_hi:[1,0]
	v_exp_f32_e32 v186, v186
	v_exp_f32_e32 v187, v187
	v_exp_f32_e32 v188, v188
	v_exp_f32_e32 v189, v189
	v_exp_f32_e32 v190, v190
	v_exp_f32_e32 v191, v191
	v_exp_f32_e32 v192, v192
	v_exp_f32_e32 v193, v193
	v_pk_mul_f32 v[28:29], v[28:29], v[186:187]
	v_pk_mul_f32 v[30:31], v[30:31], v[188:189]
	v_pk_mul_f32 v[24:25], v[24:25], v[190:191]
	v_pk_mul_f32 v[26:27], v[26:27], v[192:193]
	v_cvt_pk_bf16_f32 v28, v28, v29
	v_cvt_pk_bf16_f32 v29, v30, v31
	v_cvt_pk_bf16_f32 v30, v24, v25
	v_cvt_pk_bf16_f32 v31, v26, v27
	global_store_dwordx4 v202, v[28:31], s[80:81]
	s_mov_b32 s16, 0xc2c00000
	v_pk_add_f32 v[186:187], v[178:179], s[16:17] op_sel_hi:[1,0]
	v_pk_add_f32 v[188:189], v[180:181], s[16:17] op_sel_hi:[1,0]
	v_pk_add_f32 v[190:191], v[182:183], s[16:17] op_sel_hi:[1,0]
	v_pk_add_f32 v[192:193], v[184:185], s[16:17] op_sel_hi:[1,0]
	v_pk_mul_f32 v[186:187], v[186:187], v[160:161] op_sel_hi:[1,0]
	v_pk_mul_f32 v[188:189], v[188:189], v[160:161] op_sel_hi:[1,0]
	v_pk_mul_f32 v[190:191], v[190:191], v[160:161] op_sel_hi:[1,0]
	v_pk_mul_f32 v[192:193], v[192:193], v[160:161] op_sel_hi:[1,0]
	v_exp_f32_e32 v186, v186
	v_exp_f32_e32 v187, v187
	v_exp_f32_e32 v188, v188
	v_exp_f32_e32 v189, v189
	v_exp_f32_e32 v190, v190
	v_exp_f32_e32 v191, v191
	v_exp_f32_e32 v192, v192
	v_exp_f32_e32 v193, v193
	v_pk_mul_f32 v[84:85], v[84:85], v[186:187]
	v_pk_mul_f32 v[86:87], v[86:87], v[188:189]
	v_pk_mul_f32 v[80:81], v[80:81], v[190:191]
	v_pk_mul_f32 v[82:83], v[82:83], v[192:193]
	v_cvt_pk_bf16_f32 v84, v84, v85
	v_cvt_pk_bf16_f32 v85, v86, v87
	v_cvt_pk_bf16_f32 v86, v80, v81
	v_cvt_pk_bf16_f32 v87, v82, v83
	global_store_dwordx4 v201, v[84:87], s[80:81] offset:256
	v_add_u32_e32 v203, 0x18000, v196
	v_add_u32_e32 v204, 0x58000, v196
	s_mov_b32 s16, 0x42400000
	v_pk_add_f32 v[186:187], v[178:179], s[16:17] op_sel_hi:[1,0]
	v_pk_add_f32 v[188:189], v[180:181], s[16:17] op_sel_hi:[1,0]
	v_pk_add_f32 v[190:191], v[182:183], s[16:17] op_sel_hi:[1,0]
	v_pk_add_f32 v[192:193], v[184:185], s[16:17] op_sel_hi:[1,0]
	v_cmp_gt_f32_e32 vcc, 0, v186
	s_nop 1
	v_cndmask_b32_e32 v194, v149, v162, vcc
	v_cmp_gt_f32_e32 vcc, 0, v187
	v_mul_f32_e32 v186, v186, v194
	s_nop 0
	v_cndmask_b32_e32 v195, v149, v162, vcc
	v_cmp_gt_f32_e32 vcc, 0, v188
	v_mul_f32_e32 v187, v187, v195
	s_nop 0
	v_cndmask_b32_e32 v194, v149, v162, vcc
; __device__ __forceinline__ float ex2(float x) { return __builtin_amdgcn_exp2f(x); }
; __device__ __forceinline__ u32x4 pack8(const f32x4 a, const f32x4 b) { u32x4 w; w.x = pk2(a[0], a[1]); w.y = pk2(a[2], a[3]); w.z = pk2(b[0], b[1]); w.w = pk2(b[2], b[3]); return w; }
; #define PG8_BAR __builtin_amdgcn_s_barrier()
; template <class Epi, class Sched>
; __device__ __forceinline__ void gemm_phase(LAS unsigned char* lds, const Sched& S, const Epi& E) {
;     ...
;         if (!has_next) break;
;         if (!keep) {
; #pragma unroll
;             for (int a = 0; a < 2; ++a)
; #pragma unroll
;                 for (int b = 0; b < 2; ++b)
; #pragma unroll
;                     for (int m = 0; m < 4; ++m)
; #pragma unroll
;                         for (int n = 0; n < 2; ++n) acc[a][b][m][n] = (f32x4){0.f, 0.f, 0.f, 0.f};
;         }
;         cA = nA; cB = nB; nt = nnt; ++ui;
;         if (wr == 1) PG8_BAR;
;     __device__ __forceinline__ bool operator()(EPI_ARGS) const {
;     ...
;                 const int il = ROWLOC(ai, m), i = u.pm * 256 + il;
; #pragma unroll
;                 for (int bj = 0; bj < 2; ++bj) {
;                     const int j0 = u.w * 256 + COLLOC(bj);
;                     f32x4 p[2];
; #pragma unroll
;                     for (int n = 0; n < 2; ++n)
; #pragma unroll
;                         for (int e = 0; e < 4; ++e) { const int d = i - (j0 + 4 * n + e); const float w = ex2(d >= 0 ? (float)d * lgf : (float)(-d) * lgb); p[n][e] = acc[ai][bj][m][n][e] * w; }
;                     *(u32x4*)(pscr + (size_t)il * D + j0) = pack8(p[0], p[1]);
;                 }
	v_cmp_gt_f32_e32 vcc, 0, v189
	v_mul_f32_e32 v188, v188, v194
	s_nop 0
	v_cndmask_b32_e32 v195, v149, v162, vcc
	v_cmp_gt_f32_e32 vcc, 0, v190
	v_mul_f32_e32 v189, v189, v195
	s_nop 0
	v_cndmask_b32_e32 v194, v149, v162, vcc
	v_cmp_gt_f32_e32 vcc, 0, v191
	v_mul_f32_e32 v190, v190, v194
	s_nop 0
	v_cndmask_b32_e32 v195, v149, v162, vcc
	v_cmp_gt_f32_e32 vcc, 0, v192
	v_mul_f32_e32 v191, v191, v195
	s_nop 0
	v_cndmask_b32_e32 v194, v149, v162, vcc
	v_cmp_gt_f32_e32 vcc, 0, v193
	v_mul_f32_e32 v192, v192, v194
	s_nop 0
	v_cndmask_b32_e32 v195, v149, v162, vcc
	v_mul_f32_e32 v193, v193, v195
	v_exp_f32_e32 v186, v186
	v_exp_f32_e32 v187, v187
	v_exp_f32_e32 v188, v188
	v_exp_f32_e32 v189, v189
	v_exp_f32_e32 v190, v190
	v_exp_f32_e32 v191, v191
	v_exp_f32_e32 v192, v192
	v_exp_f32_e32 v193, v193
	v_pk_mul_f32 v[76:77], v[76:77], v[186:187]
	v_pk_mul_f32 v[78:79], v[78:79], v[188:189]
	v_pk_mul_f32 v[72:73], v[72:73], v[190:191]
	v_pk_mul_f32 v[74:75], v[74:75], v[192:193]
	v_cvt_pk_bf16_f32 v76, v76, v77
	v_cvt_pk_bf16_f32 v77, v78, v79
	v_cvt_pk_bf16_f32 v78, v72, v73
	v_cvt_pk_bf16_f32 v79, v74, v75
	global_store_dwordx4 v203, v[76:79], s[80:81]
	v_pk_mul_f32 v[4:5], v[4:5], v[186:187]
	v_pk_mul_f32 v[6:7], v[6:7], v[188:189]
	v_pk_mul_f32 v[0:1], v[0:1], v[190:191]
	v_pk_mul_f32 v[2:3], v[2:3], v[192:193]
	v_cvt_pk_bf16_f32 v4, v4, v5
	v_cvt_pk_bf16_f32 v5, v6, v7
	v_cvt_pk_bf16_f32 v6, v0, v1
	v_cvt_pk_bf16_f32 v7, v2, v3
	global_store_dwordx4 v204, v[4:7], s[80:81] offset:256
	s_mov_b32 s16, 0x43300000
	v_pk_add_f32 v[186:187], v[178:179], s[16:17] op_sel_hi:[1,0]
	v_pk_add_f32 v[188:189], v[180:181], s[16:17] op_sel_hi:[1,0]
	v_pk_add_f32 v[190:191], v[182:183], s[16:17] op_sel_hi:[1,0]
	v_pk_add_f32 v[192:193], v[184:185], s[16:17] op_sel_hi:[1,0]
	v_pk_mul_f32 v[186:187], v[186:187], v[158:159] op_sel_hi:[1,0]
	v_pk_mul_f32 v[188:189], v[188:189], v[158:159] op_sel_hi:[1,0]
	v_pk_mul_f32 v[190:191], v[190:191], v[158:159] op_sel_hi:[1,0]
	v_pk_mul_f32 v[192:193], v[192:193], v[158:159] op_sel_hi:[1,0]
	v_exp_f32_e32 v186, v186
	v_exp_f32_e32 v187, v187
	v_exp_f32_e32 v188, v188
	v_exp_f32_e32 v189, v189
	v_exp_f32_e32 v190, v190
	v_exp_f32_e32 v191, v191
	v_exp_f32_e32 v192, v192
	v_exp_f32_e32 v193, v193
	v_pk_mul_f32 v[12:13], v[12:13], v[186:187]
	v_pk_mul_f32 v[14:15], v[14:15], v[188:189]
	v_pk_mul_f32 v[8:9], v[8:9], v[190:191]
	v_pk_mul_f32 v[10:11], v[10:11], v[192:193]
	v_cvt_pk_bf16_f32 v12, v12, v13
	v_cvt_pk_bf16_f32 v13, v14, v15
	v_cvt_pk_bf16_f32 v14, v8, v9
	v_cvt_pk_bf16_f32 v15, v10, v11
	global_store_dwordx4 v204, v[12:15], s[80:81]
	s_mov_b32 s16, 0xc2a00000
	v_pk_add_f32 v[186:187], v[178:179], s[16:17] op_sel_hi:[1,0]
	v_pk_add_f32 v[188:189], v[180:181], s[16:17] op_sel_hi:[1,0]
	v_pk_add_f32 v[190:191], v[182:183], s[16:17] op_sel_hi:[1,0]
	v_pk_add_f32 v[192:193], v[184:185], s[16:17] op_sel_hi:[1,0]
	v_pk_mul_f32 v[186:187], v[186:187], v[160:161] op_sel_hi:[1,0]
	v_pk_mul_f32 v[188:189], v[188:189], v[160:161] op_sel_hi:[1,0]
	v_pk_mul_f32 v[190:191], v[190:191], v[160:161] op_sel_hi:[1,0]
	v_pk_mul_f32 v[192:193], v[192:193], v[160:161] op_sel_hi:[1,0]
	v_exp_f32_e32 v186, v186
	v_exp_f32_e32 v187, v187
	v_exp_f32_e32 v188, v188
	v_exp_f32_e32 v189, v189
	v_exp_f32_e32 v190, v190
	v_exp_f32_e32 v191, v191
	v_exp_f32_e32 v192, v192
	v_exp_f32_e32 v193, v193
	v_pk_mul_f32 v[68:69], v[68:69], v[186:187]
	v_pk_mul_f32 v[70:71], v[70:71], v[188:189]
	v_pk_mul_f32 v[64:65], v[64:65], v[190:191]
	v_pk_mul_f32 v[66:67], v[66:67], v[192:193]
	v_cvt_pk_bf16_f32 v68, v68, v69
	v_cvt_pk_bf16_f32 v69, v70, v71
	v_cvt_pk_bf16_f32 v70, v64, v65
	v_cvt_pk_bf16_f32 v71, v66, v67
	global_store_dwordx4 v203, v[68:71], s[80:81] offset:256
	s_mov_b64 s[16:17], -1
	s_andn2_b64 vcc, exec, s[6:7]
	s_cbranch_vccnz .LBB0_830
	s_andn2_b64 vcc, exec, s[78:79]
	s_cbranch_vccnz .LBB0_829
	s_barrier
	s_branch .LBB0_829
